# P6 task: K and Q row loads (24 x4 loads) issued at task start, in flight together with the g/beta loads, instead of after the cumsum
# speedup vs baseline: 1.0032x; 1.0011x over previous
.LBB0_686:
	s_and_b32 s4, s33, 63
	s_lshr_b32 s0, s33, 6
	s_ashr_i32 s20, s33, 11
	s_bfe_u32 s37, s0, 0x40001
	s_lshl_b32 s0, s20, 12
	v_writelane_b32 v250, s4, 13
	s_lshl_b32 s4, s4, 6
	v_mov_b32_e32 v126, v190
	s_or_b32 s0, s0, s4
	s_lshl_b32 s98, s37, 8
	v_readlane_b32 s96, v251, 61
	v_readlane_b32 s97, v251, 63
	v_and_b32_e32 v244, 31, v190
	v_lshrrev_b32_e32 v246, 5, v190
	s_add_u32 s96, s96, s98
	s_addc_u32 s97, s97, 0
	v_lshlrev_b32_e32 v246, 4, v246
	v_mov_b32_e32 v247, 0
	v_or_b32_e32 v244, s0, v244
	v_ashrrev_i32_e32 v245, 31, v244
	v_or_b32_e32 v248, 32, v244
	v_ashrrev_i32_e32 v249, 31, v248
	v_lshlrev_b64 v[244:245], 12, v[244:245]
	v_lshlrev_b64 v[248:249], 12, v[248:249]
	v_lshl_add_u64 v[244:245], v[244:245], 0, v[246:247]
	v_lshl_add_u64 v[248:249], v[248:249], 0, v[246:247]
	v_lshl_add_u64 v[246:247], v[244:245], 0, s[96:97]
	v_lshl_add_u64 v[248:249], v[248:249], 0, s[96:97]
	v_readlane_b32 s96, v250, 1
	v_readlane_b32 s97, v250, 2
	s_add_u32 s96, s96, s98
	s_addc_u32 s97, s97, 0
	s_nop 0
	v_lshl_add_u64 v[244:245], v[244:245], 0, s[96:97]
	global_load_dwordx4 v[50:53], v[246:247], off
	global_load_dwordx4 v[102:105], v[246:247], off offset:32
	global_load_dwordx4 v[94:97], v[246:247], off offset:64
	global_load_dwordx4 v[86:89], v[246:247], off offset:96
	global_load_dwordx4 v[78:81], v[246:247], off offset:128
	global_load_dwordx4 v[74:77], v[246:247], off offset:160
	global_load_dwordx4 v[70:73], v[246:247], off offset:192
	global_load_dwordx4 v[66:69], v[246:247], off offset:224
	global_load_dwordx4 v[54:57], v[248:249], off
	global_load_dwordx4 v[118:121], v[248:249], off offset:32
	global_load_dwordx4 v[114:117], v[248:249], off offset:64
	global_load_dwordx4 v[110:113], v[248:249], off offset:96
	global_load_dwordx4 v[106:109], v[248:249], off offset:128
	global_load_dwordx4 v[98:101], v[248:249], off offset:160
	global_load_dwordx4 v[90:93], v[248:249], off offset:192
	global_load_dwordx4 v[82:85], v[248:249], off offset:224
	global_load_dwordx4 v[228:231], v[244:245], off
	global_load_dwordx4 v[168:171], v[244:245], off offset:32
	global_load_dwordx4 v[176:179], v[244:245], off offset:64
	global_load_dwordx4 v[212:215], v[244:245], off offset:96
	global_load_dwordx4 v[216:219], v[244:245], off offset:128
	global_load_dwordx4 v[220:223], v[244:245], off offset:160
	global_load_dwordx4 v[236:239], v[244:245], off offset:192
	global_load_dwordx4 v[240:243], v[244:245], off offset:224
	s_bfe_u32 s1, s33, 0x50006
	v_add_u32_e32 v2, s0, v126
	v_ashrrev_i32_e32 v3, 31, v2
	v_lshlrev_b64 v[2:3], 7, v[2:3]
	v_readlane_b32 s4, v251, 57
	v_lshl_or_b32 v2, s1, 2, v2
	v_readlane_b32 s5, v251, 58
	v_cmp_lt_i32_e32 vcc, 0, v126
	s_movk_i32 s1, 0x80
	v_lshl_add_u64 v[4:5], s[4:5], 0, v[2:3]
	global_load_dword v4, v[4:5], off
	v_readlane_b32 s4, v251, 59
	v_readlane_b32 s5, v251, 60
	v_readlane_b32 s6, v251, 55
	v_ashrrev_i32_e32 v127, 31, v126
	v_lshl_add_u64 v[2:3], s[4:5], 0, v[2:3]
	global_load_dword v193, v[2:3], off
	v_lshlrev_b32_e32 v2, 2, v126
	v_add_u32_e32 v3, 0xfc, v2
	v_and_b32_e32 v3, 0xfc, v3
	s_add_u32 s4, s94, s7
	s_addc_u32 s5, s95, s8
	v_and_b32_e32 v192, 31, v126
	s_waitcnt vmcnt(0)
	v_ashrrev_i32_e32 v63, 5, v126
	v_lshlrev_b32_e32 v128, 3, v63
	v_ashrrev_i32_e32 v129, 31, v128
	v_lshl_add_u32 v62, v192, 2, s6
	v_writelane_b32 v250, s7, 15
	v_mov_b32_e32 v194, 0
	v_writelane_b32 v250, s8, 17
	ds_bpermute_b32 v3, v3, v4
	s_waitcnt lgkmcnt(0)
	v_cndmask_b32_e32 v3, 0, v3, vcc
	v_add_f32_e32 v3, v4, v3
	v_add_u32_e32 v4, 0xf8, v2
	v_and_b32_e32 v4, 0xfc, v4
	ds_bpermute_b32 v4, v4, v3
	v_cmp_lt_i32_e32 vcc, 1, v126
	s_waitcnt lgkmcnt(0)
	s_nop 0
	v_cndmask_b32_e32 v4, 0, v4, vcc
	v_add_f32_e32 v3, v3, v4
	v_add_u32_e32 v4, 0xf0, v2
	v_and_b32_e32 v4, 0xfc, v4
	ds_bpermute_b32 v4, v4, v3
	v_cmp_lt_i32_e32 vcc, 3, v126
	s_waitcnt lgkmcnt(0)
	s_nop 0
	v_cndmask_b32_e32 v4, 0, v4, vcc
	v_add_f32_e32 v3, v3, v4
	v_add_u32_e32 v4, 0xe0, v2
	v_and_b32_e32 v4, 0xfc, v4
	ds_bpermute_b32 v4, v4, v3
	v_cmp_lt_i32_e32 vcc, 7, v126
	s_waitcnt lgkmcnt(0)
	s_nop 0
	v_cndmask_b32_e32 v4, 0, v4, vcc
	v_add_f32_e32 v3, v3, v4
	v_add_u32_e32 v4, 0xc0, v2
	v_and_b32_e32 v4, 0xfc, v4
	ds_bpermute_b32 v4, v4, v3
	v_cmp_lt_i32_e32 vcc, 15, v126
	s_waitcnt lgkmcnt(0)
	s_nop 0
	v_cndmask_b32_e32 v4, 0, v4, vcc
	v_add_f32_e32 v3, v3, v4
	v_bitop3_b32 v4, v2, s1, v191 bitop3:0x6c
	ds_bpermute_b32 v4, v4, v3
	v_cmp_lt_i32_e32 vcc, 31, v126
	v_add_u32_e32 v2, s6, v2
	v_readlane_b32 s1, v251, 61
	s_waitcnt lgkmcnt(0)
	v_cndmask_b32_e32 v4, 0, v4, vcc
	v_add_f32_e32 v166, v3, v4
	ds_write2st64_b32 v2, v166, v193 offset1:1
	v_lshl_add_u64 v[2:3], v[126:127], 2, s[4:5]
	global_store_dword v[2:3], v166, off
	v_or_b32_e32 v2, s0, v192
	s_lshl_b32 s0, s37, 8
	v_ashrrev_i32_e32 v3, 31, v2
	s_add_u32 s0, s1, s0
	v_readlane_b32 s1, v251, 63
	v_lshlrev_b64 v[60:61], 12, v[2:3]
	v_or_b32_e32 v2, 32, v2
	s_addc_u32 s1, s1, 0
	v_ashrrev_i32_e32 v3, 31, v2
	v_lshl_add_u64 v[4:5], v[128:129], 1, s[0:1]
	v_lshlrev_b64 v[58:59], 12, v[2:3]
	s_waitcnt lgkmcnt(0)
	v_lshl_add_u64 v[6:7], v[4:5], 0, v[60:61]
	v_lshl_add_u64 v[2:3], v[4:5], 0, v[58:59]
	v_lshl_add_u32 v127, v63, 4, s6
	ds_read2_b32 v[130:131], v62 offset1:32
	ds_read2_b32 v[132:133], v127 offset0:32 offset1:96
	v_lshlrev_b32_e32 v62, 2, v63
	v_cmp_ge_i32_e64 s[86:87], v192, v62
	v_cmp_lt_i32_e64 s[0:1], v192, v62
	s_waitcnt vmcnt(15)
	v_mfma_f32_32x32x16_bf16 v[34:49], v[50:53], v[50:53], 0
	s_waitcnt vmcnt(7)
	v_mfma_f32_32x32x16_bf16 v[18:33], v[54:57], v[50:53], 0
	v_mfma_f32_32x32x16_bf16 v[2:17], v[54:57], v[54:57], 0
	v_mfma_f32_32x32x16_bf16 v[34:49], v[102:105], v[102:105], v[34:49]
	s_waitcnt vmcnt(6)
	v_mfma_f32_32x32x16_bf16 v[18:33], v[118:121], v[102:105], v[18:33]
	v_mfma_f32_32x32x16_bf16 v[2:17], v[118:121], v[118:121], v[2:17]
	v_mfma_f32_32x32x16_bf16 v[34:49], v[94:97], v[94:97], v[34:49]
	s_waitcnt vmcnt(5)
	v_mfma_f32_32x32x16_bf16 v[18:33], v[114:117], v[94:97], v[18:33]
	v_mfma_f32_32x32x16_bf16 v[2:17], v[114:117], v[114:117], v[2:17]
	v_mfma_f32_32x32x16_bf16 v[34:49], v[86:89], v[86:89], v[34:49]
	s_waitcnt vmcnt(4)
	v_mfma_f32_32x32x16_bf16 v[18:33], v[110:113], v[86:89], v[18:33]
	v_mfma_f32_32x32x16_bf16 v[2:17], v[110:113], v[110:113], v[2:17]
	v_mfma_f32_32x32x16_bf16 v[34:49], v[78:81], v[78:81], v[34:49]
	s_waitcnt vmcnt(3)
	v_mfma_f32_32x32x16_bf16 v[18:33], v[106:109], v[78:81], v[18:33]
	v_mfma_f32_32x32x16_bf16 v[2:17], v[106:109], v[106:109], v[2:17]
	v_mfma_f32_32x32x16_bf16 v[34:49], v[74:77], v[74:77], v[34:49]
	s_waitcnt vmcnt(2)
	v_mfma_f32_32x32x16_bf16 v[18:33], v[98:101], v[74:77], v[18:33]
	v_mfma_f32_32x32x16_bf16 v[2:17], v[98:101], v[98:101], v[2:17]
	v_mfma_f32_32x32x16_bf16 v[34:49], v[70:73], v[70:73], v[34:49]
	s_waitcnt vmcnt(1)
	v_mfma_f32_32x32x16_bf16 v[18:33], v[90:93], v[70:73], v[18:33]
	v_mfma_f32_32x32x16_bf16 v[2:17], v[90:93], v[90:93], v[2:17]
	v_mfma_f32_32x32x16_bf16 v[34:49], v[66:69], v[66:69], v[34:49]
	s_waitcnt vmcnt(0)
	v_mfma_f32_32x32x16_bf16 v[18:33], v[82:85], v[66:69], v[18:33]
	v_mfma_f32_32x32x16_bf16 v[2:17], v[82:85], v[82:85], v[2:17]
	s_and_saveexec_b64 s[4:5], s[0:1]
	s_cbranch_execz .LBB0_688
	ds_read2st64_b32 v[64:65], v127 offset1:1
	s_waitcnt lgkmcnt(0)
	v_sub_f32_e32 v63, v64, v130
	v_mul_f32_e32 v63, 0x3fb8aa3b, v63
	v_exp_f32_e32 v63, v63
	s_nop 1
	v_mul_f32_e32 v34, v34, v65
	v_mul_f32_e32 v194, v34, v63

.LBB0_718:
	s_or_b64 exec, exec, s[96:97]
	v_readlane_b32 s96, v250, 1
	s_lshl_b32 s12, s37, 7
	v_readlane_b32 s97, v250, 2
	s_lshl_b32 s12, s12, 1
	s_nop 0
	v_lshl_add_u64 v[34:35], s[96:97], 0, v[60:61]
	v_lshl_add_u64 v[34:35], v[34:35], 0, s[12:13]
	v_lshl_add_u64 v[60:61], v[128:129], 1, v[34:35]
	s_waitcnt vmcnt(7)
	v_mfma_f32_32x32x16_bf16 v[34:49], v[50:53], v[228:231], 0
	s_waitcnt vmcnt(6)
	v_mfma_f32_32x32x16_bf16 v[34:49], v[102:105], v[168:171], v[34:49]
	s_waitcnt vmcnt(5)
	v_mfma_f32_32x32x16_bf16 v[34:49], v[94:97], v[176:179], v[34:49]
	s_waitcnt vmcnt(4)
	v_mfma_f32_32x32x16_bf16 v[34:49], v[86:89], v[212:215], v[34:49]
	s_waitcnt vmcnt(3)
	v_mfma_f32_32x32x16_bf16 v[34:49], v[78:81], v[216:219], v[34:49]
	s_waitcnt vmcnt(2)
	v_mfma_f32_32x32x16_bf16 v[34:49], v[74:77], v[220:223], v[34:49]
	s_waitcnt vmcnt(1)
	v_mfma_f32_32x32x16_bf16 v[34:49], v[70:73], v[236:239], v[34:49]
	s_waitcnt vmcnt(0)
	v_mfma_f32_32x32x16_bf16 v[34:49], v[66:69], v[240:243], v[34:49]
	s_and_saveexec_b64 s[96:97], s[86:87]
	s_cbranch_execz .LBB0_720
	ds_read_b32 v60, v127
	s_nop 8
	v_mul_f32_e32 v34, 0x3db504f3, v34
	s_waitcnt lgkmcnt(0)
	v_sub_f32_e32 v60, v130, v60
	v_mul_f32_e32 v60, 0x3fb8aa3b, v60
	v_exp_f32_e32 v60, v60
	s_nop 0
	v_mul_f32_e32 v64, v34, v60
